# v105 + filter-MLP weight staging hand-written: all loads in flight at once (was six serial round trips, 600 lines)
# speedup vs baseline: 1.0065x; 1.0007x over previous
.Lp0_F:
	s_nop 0
	v_mov_b32_e32 v0, v179
	s_barrier
	s_barrier
	v_readlane_b32 s56, v252, 20
	v_readlane_b32 s57, v252, 21
	v_readlane_b32 s58, v252, 24
	v_readlane_b32 s59, v252, 25
	v_readlane_b32 s60, v252, 22
	v_readlane_b32 s61, v252, 23
	v_readlane_b32 s2, v254, 62
	v_readlane_b32 s3, v254, 63
	v_lshlrev_b32_e32 v1, 2, v0
	v_add_u32_e32 v24, 0x1000, v1
	v_add_u32_e32 v25, 0x2000, v1
	v_add_u32_e32 v26, 0x3000, v1
	v_add_u32_e32 v27, 0x4000, v1
	v_add_u32_e32 v28, 0x5000, v1
	v_add_u32_e32 v29, 0x6000, v1
	v_add_u32_e32 v30, 0x7000, v1
	global_load_dword v2, v1, s[56:57]
	global_load_dword v3, v1, s[56:57] offset:2048
	global_load_dword v4, v24, s[56:57]
	global_load_dword v5, v24, s[56:57] offset:2048
	global_load_dword v32, v1, s[58:59]
	global_load_dword v33, v1, s[58:59] offset:2048
	global_load_dword v34, v24, s[58:59]
	global_load_dword v35, v24, s[58:59] offset:2048
	global_load_dword v36, v25, s[58:59]
	global_load_dword v37, v25, s[58:59] offset:2048
	global_load_dword v38, v26, s[58:59]
	global_load_dword v39, v26, s[58:59] offset:2048
	global_load_dword v40, v27, s[58:59]
	global_load_dword v41, v27, s[58:59] offset:2048
	global_load_dword v42, v28, s[58:59]
	global_load_dword v43, v28, s[58:59] offset:2048
	global_load_dword v44, v29, s[58:59]
	global_load_dword v45, v29, s[58:59] offset:2048
	global_load_dword v46, v30, s[58:59]
	global_load_dword v47, v30, s[58:59] offset:2048
	s_movk_i32 s6, 0x80
	v_cmp_gt_u32_e32 vcc, s6, v0
	s_and_saveexec_b64 s[6:7], vcc
	global_load_dword v9, v1, s[76:77]
	s_mov_b64 exec, s[6:7]
	v_cmp_gt_u32_e32 vcc, 64, v0
	s_and_saveexec_b64 s[6:7], vcc
	global_load_dword v6, v25, s[56:57]
	global_load_dword v7, v1, s[60:61]
	global_load_dword v8, v1, s[78:79]
	s_mov_b64 exec, s[6:7]
	v_add_u32_e32 v10, s2, v1
	v_add_u32_e32 v11, s3, v1
	s_waitcnt vmcnt(0)
	ds_write_b32 v10, v2
	ds_write_b32 v10, v3 offset:2048
	ds_write_b32 v10, v4 offset:4096
	ds_write_b32 v10, v5 offset:6144
	ds_write_b32 v11, v32
	ds_write_b32 v11, v33 offset:2048
	ds_write_b32 v11, v34 offset:4096
	ds_write_b32 v11, v35 offset:6144
	ds_write_b32 v11, v36 offset:8192
	ds_write_b32 v11, v37 offset:10240
	ds_write_b32 v11, v38 offset:12288
	ds_write_b32 v11, v39 offset:14336
	ds_write_b32 v11, v40 offset:16384
	ds_write_b32 v11, v41 offset:18432
	ds_write_b32 v11, v42 offset:20480
	ds_write_b32 v11, v43 offset:22528
	ds_write_b32 v11, v44 offset:24576
	ds_write_b32 v11, v45 offset:26624
	ds_write_b32 v11, v46 offset:28672
	ds_write_b32 v11, v47 offset:30720
	s_movk_i32 s6, 0x80
	v_cmp_gt_u32_e32 vcc, s6, v0
	s_and_saveexec_b64 s[6:7], vcc
	ds_write_b32 v1, v9 offset:55936
	s_mov_b64 exec, s[6:7]
	v_cmp_gt_u32_e32 vcc, 64, v0
	s_and_saveexec_b64 s[6:7], vcc
	ds_write_b32 v10, v6 offset:8192
	ds_write_b32 v1, v7 offset:55680
	ds_write_b32 v1, v8 offset:56448
	s_mov_b64 exec, s[6:7]
	s_waitcnt lgkmcnt(0)
